# NA phase: one static s_setprio 1 for the younger half (waves 4-7) at phase entry, back to 0 at exit (asm guide 7.4)
# speedup vs baseline: 1.0111x; 1.0111x over previous
.LBB0_227:
	s_or_b64 exec, exec, s[6:7]
	s_lshr_b32 s10, s22, 1
	s_mov_b64 s[6:7], -1
	s_and_b64 vcc, exec, s[4:5]
	s_waitcnt lgkmcnt(0)
	s_barrier
	s_cbranch_vccz .LBB0_331
	s_movk_i32 s41, 0x480
	s_cmp_eq_u32 s22, 3
	s_cselect_b32 s41, 0x400, s41
	s_mov_b32 s53, 0x3e0293ee
	v_readlane_b32 s24, v253, 8
	v_readlane_b32 s25, v253, 9
	s_mul_i32 s1, s10, 0xe880
	s_add_u32 s24, s24, s1
	s_addc_u32 s25, s25, 0
	s_add_u32 s26, s92, 0x18e00000
	s_addc_u32 s27, s93, 0
	s_add_u32 s28, s92, 0x2ae00000
	s_addc_u32 s29, s93, 0
	v_readfirstlane_b32 s36, v172
	s_lshr_b32 s36, s36, 6
	s_and_b32 s37, s36, 3
	s_lshr_b32 s38, s36, 2
	s_cmp_lt_u32 s36, 4
	s_cbranch_scc1 .Lna_noprio
	s_setprio 1
.Lna_noprio:
	s_lshl_b32 s39, s37, 3
	s_cmp_gt_u32 s37, 1
	s_cselect_b32 s1, 8, 0
	s_add_u32 s39, s39, s1
	v_and_b32_e32 v192, 15, v246
	v_lshrrev_b32_e32 v193, 4, v246
	v_lshrrev_b32_e32 v224, 4, v172
	v_and_b32_e32 v225, 15, v172
	v_lshlrev_b32_e32 v194, 15, v224
	v_lshl_add_u32 v194, v225, 4, v194
	v_add_u32_e32 v195, 0x100000, v194
	v_mul_u32_u24_e32 v196, 0x120, v224
	v_lshl_add_u32 v196, v225, 4, v196
	v_mul_u32_u24_e32 v197, 0x120, v224
	v_lshl_add_u32 v197, v225, 4, v197
	v_add_u32_e32 v197, 0x4800, v197
	v_mul_u32_u24_e32 v199, 0x120, v192
	v_lshl_add_u32 v199, v193, 4, v199
	s_mul_i32 s1, s39, 0x120
	v_add_u32_e32 v198, s1, v199
	v_lshrrev_b32_e32 v224, 2, v192
	v_lshl_add_u32 v224, v193, 2, v224
	v_mul_u32_u24_e32 v201, 0x120, v224
	v_and_b32_e32 v225, 3, v192
	v_lshl_add_u32 v201, v225, 3, v201
	v_add_u32_e32 v201, 0x4800, v201
	s_mul_i32 s1, s39, 0x120
	v_add_u32_e32 v200, s1, v201
	v_lshl_add_u32 v228, s37, 4, v192
	v_add_u32_e32 v224, -8, v228
	v_max_i32_e32 v224, 0, v224
	v_min_i32_e32 v229, 48, v224
	v_lshl_add_u32 v230, v193, 2, s39
	v_add_u32_e32 v224, 0, v230
	v_sub_u32_e32 v225, v224, v229
	v_cmp_gt_u32_e32 vcc, 16, v225
	v_sub_u32_e32 v224, v224, v228
	v_add_u32_e32 v224, 15, v224
	v_cndmask_b32_e32 v224, 31, v224, vcc
	v_lshlrev_b32_e32 v202, 2, v224
	v_add_u32_e32 v224, 1, v230
	v_sub_u32_e32 v225, v224, v229
	v_cmp_gt_u32_e32 vcc, 16, v225
	v_sub_u32_e32 v224, v224, v228
	v_add_u32_e32 v224, 15, v224
	v_cndmask_b32_e32 v224, 31, v224, vcc
	v_lshlrev_b32_e32 v203, 2, v224
	v_add_u32_e32 v224, 2, v230
	v_sub_u32_e32 v225, v224, v229
	v_cmp_gt_u32_e32 vcc, 16, v225
	v_sub_u32_e32 v224, v224, v228
	v_add_u32_e32 v224, 15, v224
	v_cndmask_b32_e32 v224, 31, v224, vcc
	v_lshlrev_b32_e32 v204, 2, v224
	v_add_u32_e32 v224, 3, v230
	v_sub_u32_e32 v225, v224, v229
	v_cmp_gt_u32_e32 vcc, 16, v225
	v_sub_u32_e32 v224, v224, v228
	v_add_u32_e32 v224, 15, v224
	v_cndmask_b32_e32 v224, 31, v224, vcc
	v_lshlrev_b32_e32 v205, 2, v224
	v_add_u32_e32 v224, 16, v230
	v_sub_u32_e32 v225, v224, v229
	v_cmp_gt_u32_e32 vcc, 16, v225
	v_sub_u32_e32 v224, v224, v228
	v_add_u32_e32 v224, 15, v224
	v_cndmask_b32_e32 v224, 31, v224, vcc
	v_lshlrev_b32_e32 v206, 2, v224
	v_add_u32_e32 v224, 17, v230
	v_sub_u32_e32 v225, v224, v229
	v_cmp_gt_u32_e32 vcc, 16, v225
	v_sub_u32_e32 v224, v224, v228
	v_add_u32_e32 v224, 15, v224
	v_cndmask_b32_e32 v224, 31, v224, vcc
	v_lshlrev_b32_e32 v207, 2, v224
	v_add_u32_e32 v224, 18, v230
	v_sub_u32_e32 v225, v224, v229
	v_cmp_gt_u32_e32 vcc, 16, v225
	v_sub_u32_e32 v224, v224, v228
	v_add_u32_e32 v224, 15, v224
	v_cndmask_b32_e32 v224, 31, v224, vcc
	v_lshlrev_b32_e32 v208, 2, v224
	v_add_u32_e32 v224, 19, v230
	v_sub_u32_e32 v225, v224, v229
	v_cmp_gt_u32_e32 vcc, 16, v225
	v_sub_u32_e32 v224, v224, v228
	v_add_u32_e32 v224, 15, v224
	v_cndmask_b32_e32 v224, 31, v224, vcc
	v_lshlrev_b32_e32 v209, 2, v224
	v_lshlrev_b32_e32 v210, 15, v192
	v_lshl_add_u32 v210, v193, 4, v210
	v_lshlrev_b32_e32 v211, 15, v192
	v_lshl_add_u32 v211, v193, 3, v211
	v_and_b32_e32 v224, 1, v193
	v_mul_u32_u24_e32 v224, 24, v224
	v_add_u32_e32 v211, v211, v224
	v_lshlrev_b32_e32 v212, 13, v192
	v_lshl_add_u32 v212, v193, 3, v212
	v_add_u32_e32 v212, v212, v224
	v_lshrrev_b32_e32 v224, 5, v172
	v_and_b32_e32 v225, 31, v172
	v_cmp_gt_u32_e32 vcc, 15, v224
	v_cmp_gt_u32_e64 s[22:23], 31, v225
	s_and_b64 s[22:23], s[22:23], vcc
	v_mul_u32_u24_e32 v224, 31, v224
	v_add_lshl_u32 v224, v224, v225, 2
	v_cndmask_b32_e64 v213, 0, v224, s[22:23]
	v_lshlrev_b32_e32 v214, 2, v172
	v_add_u32_e32 v214, 0x12000, v214
	v_xor_b32_e32 v215, 16, v246
	v_lshlrev_b32_e32 v215, 2, v215
	v_xor_b32_e32 v216, 32, v246
	v_lshlrev_b32_e32 v216, 2, v216
	v_xor_b32_e32 v217, 48, v246
	v_lshlrev_b32_e32 v217, 2, v217
	s_mov_b32 s40, s62
	s_cmp_ge_u32 s40, 0x400
	s_cbranch_scc1 .Lna_dec_ctx_0
	s_mov_b32 s45, 0
	s_cmp_eq_u32 s94, 0x100
	s_cbranch_scc0 .Lna_dec_gen_0
	s_lshr_b32 s1, s40, 8
	s_and_b32 s2, s40, 0xff
	s_lshl_b32 s1, s1, 5
	s_and_b32 s4, s2, 7
	s_lshl_b32 s4, s4, 2
	s_add_u32 s1, s1, s4
	s_lshr_b32 s4, s2, 6
	s_add_u32 s1, s1, s4
	s_bfe_u32 s44, s2, 0x30003
	s_lshr_b32 s4, s40, 7
	s_and_b32 s4, s4, 6
	s_add_u32 s44, s44, s4
	s_and_b32 s44, s44, 7
	s_branch .Lna_dec_l2_0

.Lna_done:
	s_waitcnt vmcnt(0)
	s_setprio 0
